# sample-attention K/V loop: s_sleep 32 at the top of each of the 7 row-batch iterations (throttles the SA items HBM request rate; less contention for prompt attention)
# baseline (speedup 1.0000x reference)
.LBB0_471:
	s_sleep 32
	v_add_u32_e32 v84, s2, v101
	v_and_b32_e32 v85, -16, v163
	s_movk_i32 s0, 0x180
	v_or_b32_e32 v36, v85, v159
	v_add_u32_e32 v37, 0x480, v84
	v_cmp_gt_i32_e32 vcc, s0, v84
	v_add_u32_e32 v52, v160, v85
	v_add_u32_e32 v53, 0x4a0, v84
	v_cndmask_b32_e32 v177, v37, v36, vcc
	v_mad_u64_u32 v[44:45], s[0:1], v177, s19, v[136:137]
	s_movk_i32 s0, 0x160
	s_nop 0
	v_cmp_gt_i32_e32 vcc, s0, v84
	v_add_u32_e32 v68, v161, v85
	v_add_u32_e32 v69, 0x4c0, v84
	v_cndmask_b32_e32 v176, v53, v52, vcc
	v_mad_u64_u32 v[60:61], s[0:1], v176, s19, v[136:137]
	s_movk_i32 s0, 0x140
	s_nop 0
	v_cmp_gt_i32_e32 vcc, s0, v84
	v_add_u32_e32 v85, v162, v85
	v_add_u32_e32 v86, 0x4e0, v84
	v_cndmask_b32_e32 v173, v69, v68, vcc
	v_mad_u64_u32 v[76:77], s[0:1], v173, s19, v[136:137]
	s_movk_i32 s0, 0x120
	s_nop 0
	v_cmp_gt_i32_e32 vcc, s0, v84
	v_add_u32_e32 v48, 0x1000, v44
	v_add_u32_e32 v64, 0x1000, v60
	v_cndmask_b32_e32 v172, v86, v85, vcc
	v_mad_u64_u32 v[92:93], s[0:1], v172, s19, v[136:137]
	v_add_u32_e32 v80, 0x1000, v76
	v_add_u32_e32 v96, 0x1000, v92
	buffer_load_dwordx4 v[36:39], v44, s[8:11], 0 offen sc0 nt sc1
	buffer_load_dwordx4 v[40:43], v44, s[8:11], 0 offen offset:256 sc0 nt sc1
	s_nop 0
	buffer_load_dwordx4 v[44:47], v48, s[8:11], 0 offen offset:2048 sc0 nt sc1
	s_nop 0
	buffer_load_dwordx4 v[48:51], v48, s[8:11], 0 offen offset:2304 sc0 nt sc1
	s_nop 0
	buffer_load_dwordx4 v[52:55], v60, s[8:11], 0 offen sc0 nt sc1
	buffer_load_dwordx4 v[56:59], v60, s[8:11], 0 offen offset:256 sc0 nt sc1
	s_nop 0
	buffer_load_dwordx4 v[60:63], v64, s[8:11], 0 offen offset:2048 sc0 nt sc1
	s_nop 0
	buffer_load_dwordx4 v[64:67], v64, s[8:11], 0 offen offset:2304 sc0 nt sc1
	s_nop 0
	buffer_load_dwordx4 v[68:71], v76, s[8:11], 0 offen sc0 nt sc1
	buffer_load_dwordx4 v[72:75], v76, s[8:11], 0 offen offset:256 sc0 nt sc1
	s_nop 0
	buffer_load_dwordx4 v[76:79], v80, s[8:11], 0 offen offset:2048 sc0 nt sc1
	s_nop 0
	buffer_load_dwordx4 v[80:83], v80, s[8:11], 0 offen offset:2304 sc0 nt sc1
	s_nop 0
	buffer_load_dwordx4 v[84:87], v92, s[8:11], 0 offen sc0 nt sc1
	buffer_load_dwordx4 v[88:91], v92, s[8:11], 0 offen offset:256 sc0 nt sc1
	s_nop 0
	buffer_load_dwordx4 v[92:95], v96, s[8:11], 0 offen offset:2048 sc0 nt sc1
	s_nop 0
	buffer_load_dwordx4 v[96:99], v96, s[8:11], 0 offen offset:2304 sc0 nt sc1
	s_waitcnt vmcnt(15)
	v_mul_f32_e32 v114, v37, v158
	v_fmac_f32_e32 v114, v36, v157
	v_fmac_f32_e32 v114, v38, v134
	v_fmac_f32_e32 v114, v39, v135
	s_waitcnt vmcnt(14)
	v_pk_mul_f32 v[112:113], v[40:41], v[132:133]
	v_mul_f32_e32 v115, v37, v156
	v_add_f32_e32 v112, v112, v114
	v_add_f32_e32 v114, v113, v112
	v_pk_mul_f32 v[112:113], v[42:43], v[130:131]
	v_fmac_f32_e32 v115, v36, v155
	v_add_f32_e32 v112, v112, v114
	v_add_f32_e32 v112, v113, v112
	v_fmac_f32_e32 v115, v38, v126
	v_fmac_f32_e32 v115, v39, v127
	v_add_f32_dpp v112, v112, v112 row_ror:8 row_mask:0xf bank_mask:0xf bound_ctrl:1
	v_mul_f32_e32 v128, v37, v152
	v_fmac_f32_e32 v128, v36, v151
	v_add_f32_dpp v112, v112, v112 row_ror:4 row_mask:0xf bank_mask:0xf bound_ctrl:1
	v_fmac_f32_e32 v128, v38, v110
	v_fmac_f32_e32 v128, v39, v111
	v_add_f32_dpp v168, v112, v112 row_ror:2 row_mask:0xf bank_mask:0xf bound_ctrl:1
	v_lshlrev_b32_e32 v112, 2, v177
	v_sub_u32_e32 v112, s51, v112
	v_add_u32_e32 v114, 0x2600, v112
	v_pk_mul_f32 v[112:113], v[40:41], v[124:125]
	s_waitcnt vmcnt(11)
	v_mul_f32_e32 v144, v53, v152
	v_add_f32_e32 v112, v112, v115
	v_add_f32_e32 v115, v113, v112
	v_pk_mul_f32 v[112:113], v[42:43], v[122:123]
	v_fmac_f32_e32 v144, v52, v151
	v_add_f32_e32 v112, v112, v115
	v_add_f32_e32 v112, v113, v112
	v_mul_f32_e32 v115, v37, v154
	v_fmac_f32_e32 v115, v36, v153
	v_add_f32_dpp v112, v112, v112 row_ror:8 row_mask:0xf bank_mask:0xf bound_ctrl:1
	v_fmac_f32_e32 v115, v38, v120
	v_fmac_f32_e32 v115, v39, v121
	v_add_f32_dpp v112, v112, v112 row_ror:4 row_mask:0xf bank_mask:0xf bound_ctrl:1
	v_fmac_f32_e32 v144, v54, v110
	v_fmac_f32_e32 v144, v55, v111
	v_add_f32_dpp v170, v112, v112 row_ror:2 row_mask:0xf bank_mask:0xf bound_ctrl:1
	v_pk_mul_f32 v[112:113], v[40:41], v[118:119]
	s_waitcnt vmcnt(7)
	v_mul_f32_e32 v145, v69, v156
	v_add_f32_e32 v112, v112, v115
	v_add_f32_e32 v115, v113, v112
	v_pk_mul_f32 v[112:113], v[42:43], v[116:117]
	v_fmac_f32_e32 v145, v68, v155
	v_add_f32_e32 v112, v112, v115
	v_add_f32_e32 v112, v113, v112
	v_fmac_f32_e32 v145, v70, v126
	v_fmac_f32_e32 v145, v71, v127
	v_add_f32_dpp v112, v112, v112 row_ror:8 row_mask:0xf bank_mask:0xf bound_ctrl:1
	v_mul_f32_e32 v146, v69, v152
	v_fmac_f32_e32 v146, v68, v151
	v_add_f32_dpp v112, v112, v112 row_ror:4 row_mask:0xf bank_mask:0xf bound_ctrl:1
	v_fmac_f32_e32 v146, v70, v110
	v_fmac_f32_e32 v146, v71, v111
	v_add_f32_dpp v174, v112, v112 row_ror:2 row_mask:0xf bank_mask:0xf bound_ctrl:1
	v_sub_u32_e32 v112, 2, v177
	v_lshl_add_u32 v112, v112, 2, s51
	v_add_u32_e32 v115, 0x2600, v112
	v_pk_mul_f32 v[112:113], v[40:41], v[108:109]
	s_waitcnt vmcnt(3)
	v_pk_mul_f32 v[212:213], v[86:87], v[110:111]
	v_add_f32_e32 v112, v112, v128
	v_add_f32_e32 v128, v113, v112
	v_pk_mul_f32 v[112:113], v[42:43], v[106:107]
	v_mov_b32_e32 v169, 0
	v_add_f32_e32 v112, v112, v128
	v_add_f32_e32 v112, v113, v112
	v_mul_f32_e32 v128, v53, v158
	v_fmac_f32_e32 v128, v52, v157
	v_add_f32_dpp v112, v112, v112 row_ror:8 row_mask:0xf bank_mask:0xf bound_ctrl:1
	v_fmac_f32_e32 v128, v54, v134
	v_fmac_f32_e32 v128, v55, v135
	v_add_f32_dpp v112, v112, v112 row_ror:4 row_mask:0xf bank_mask:0xf bound_ctrl:1
	v_mov_b32_e32 v171, 0
	v_mov_b32_e32 v175, 0
	v_add_f32_dpp v178, v112, v112 row_ror:2 row_mask:0xf bank_mask:0xf bound_ctrl:1
	v_pk_mul_f32 v[112:113], v[56:57], v[132:133]
	v_mov_b32_e32 v179, 0
	v_add_f32_e32 v112, v112, v128
	v_add_f32_e32 v128, v113, v112
	v_pk_mul_f32 v[112:113], v[58:59], v[130:131]
	v_mov_b32_e32 v181, 0
	v_add_f32_e32 v112, v112, v128
	v_add_f32_e32 v112, v113, v112
	v_mul_f32_e32 v128, v53, v156
	v_fmac_f32_e32 v128, v52, v155
	v_add_f32_dpp v112, v112, v112 row_ror:8 row_mask:0xf bank_mask:0xf bound_ctrl:1
	v_fmac_f32_e32 v128, v54, v126
	v_fmac_f32_e32 v128, v55, v127
	v_add_f32_dpp v112, v112, v112 row_ror:4 row_mask:0xf bank_mask:0xf bound_ctrl:1
	v_mov_b32_e32 v183, 0
	v_mov_b32_e32 v185, 0
	v_add_f32_dpp v180, v112, v112 row_ror:2 row_mask:0xf bank_mask:0xf bound_ctrl:1
	v_lshlrev_b32_e32 v112, 2, v176
	v_sub_u32_e32 v112, s51, v112
	v_add_u32_e32 v142, 0x2600, v112
	v_pk_mul_f32 v[112:113], v[56:57], v[124:125]
	v_mov_b32_e32 v187, 0
	v_add_f32_e32 v112, v112, v128
	v_add_f32_e32 v128, v113, v112
	v_pk_mul_f32 v[112:113], v[58:59], v[122:123]
	v_mov_b32_e32 v189, 0
	v_add_f32_e32 v112, v112, v128
	v_add_f32_e32 v112, v113, v112
	v_mul_f32_e32 v128, v53, v154
	v_fmac_f32_e32 v128, v52, v153
	v_add_f32_dpp v112, v112, v112 row_ror:8 row_mask:0xf bank_mask:0xf bound_ctrl:1
	v_fmac_f32_e32 v128, v54, v120
	v_fmac_f32_e32 v128, v55, v121
	v_add_f32_dpp v112, v112, v112 row_ror:4 row_mask:0xf bank_mask:0xf bound_ctrl:1
	v_mov_b32_e32 v191, 0
	v_mov_b32_e32 v193, 0
	v_add_f32_dpp v182, v112, v112 row_ror:2 row_mask:0xf bank_mask:0xf bound_ctrl:1
	v_pk_mul_f32 v[112:113], v[56:57], v[118:119]
	v_mov_b32_e32 v198, 0
	v_add_f32_e32 v112, v112, v128
	v_add_f32_e32 v128, v113, v112
	v_pk_mul_f32 v[112:113], v[58:59], v[116:117]
	v_mov_b32_e32 v200, 0
	v_add_f32_e32 v112, v112, v128
	v_add_f32_e32 v112, v113, v112
	v_mov_b32_e32 v202, 0
	v_mov_b32_e32 v210, 0
	v_add_f32_dpp v112, v112, v112 row_ror:8 row_mask:0xf bank_mask:0xf bound_ctrl:1
	v_mov_b32_dpp v169, v168 row_ror:1 row_mask:0xf bank_mask:0xf
	v_mov_b32_dpp v171, v170 row_ror:1 row_mask:0xf bank_mask:0xf
	v_add_f32_dpp v112, v112, v112 row_ror:4 row_mask:0xf bank_mask:0xf bound_ctrl:1
	v_mov_b32_dpp v175, v174 row_ror:1 row_mask:0xf bank_mask:0xf
	v_mov_b32_dpp v179, v178 row_ror:1 row_mask:0xf bank_mask:0xf
	v_add_f32_dpp v184, v112, v112 row_ror:2 row_mask:0xf bank_mask:0xf bound_ctrl:1
	v_sub_u32_e32 v112, 2, v176
	v_lshl_add_u32 v112, v112, 2, s51
	v_add_u32_e32 v112, 0x2600, v112
	ds_read2_b32 v[140:141], v114 offset1:1
	ds_read2_b32 v[128:129], v115 offset1:1
	ds_read2_b32 v[114:115], v142 offset1:1
	ds_read2_b32 v[112:113], v112 offset1:1
	v_pk_mul_f32 v[142:143], v[56:57], v[108:109]
	v_mov_b32_dpp v181, v180 row_ror:1 row_mask:0xf bank_mask:0xf
	v_add_f32_e32 v142, v142, v144
	v_add_f32_e32 v144, v143, v142
	v_pk_mul_f32 v[142:143], v[58:59], v[106:107]
	v_mov_b32_dpp v183, v182 row_ror:1 row_mask:0xf bank_mask:0xf
	v_add_f32_e32 v142, v142, v144
	v_add_f32_e32 v142, v143, v142
	v_mul_f32_e32 v144, v69, v158
	v_fmac_f32_e32 v144, v68, v157
	v_add_f32_dpp v142, v142, v142 row_ror:8 row_mask:0xf bank_mask:0xf bound_ctrl:1
	v_fmac_f32_e32 v144, v70, v134
	v_fmac_f32_e32 v144, v71, v135
	v_add_f32_dpp v142, v142, v142 row_ror:4 row_mask:0xf bank_mask:0xf bound_ctrl:1
	v_mov_b32_dpp v185, v184 row_ror:1 row_mask:0xf bank_mask:0xf
	s_nop 0
	v_add_f32_dpp v186, v142, v142 row_ror:2 row_mask:0xf bank_mask:0xf bound_ctrl:1
	v_pk_mul_f32 v[142:143], v[72:73], v[132:133]
	s_nop 0
	v_add_f32_e32 v142, v142, v144
	v_add_f32_e32 v144, v143, v142
	v_pk_mul_f32 v[142:143], v[74:75], v[130:131]
	v_mov_b32_dpp v187, v186 row_ror:1 row_mask:0xf bank_mask:0xf
	v_add_f32_e32 v142, v142, v144
	v_add_f32_e32 v142, v143, v142
	s_nop 1
	v_add_f32_dpp v142, v142, v142 row_ror:8 row_mask:0xf bank_mask:0xf bound_ctrl:1
	s_nop 1
	v_add_f32_dpp v142, v142, v142 row_ror:4 row_mask:0xf bank_mask:0xf bound_ctrl:1
	s_nop 1
	v_add_f32_dpp v188, v142, v142 row_ror:2 row_mask:0xf bank_mask:0xf bound_ctrl:1
	v_lshlrev_b32_e32 v142, 2, v173
	v_sub_u32_e32 v142, s51, v142
	v_add_u32_e32 v144, 0x2600, v142
	v_pk_mul_f32 v[142:143], v[72:73], v[124:125]
	v_mov_b32_dpp v189, v188 row_ror:1 row_mask:0xf bank_mask:0xf
	v_add_f32_e32 v142, v142, v145
	v_add_f32_e32 v145, v143, v142
	v_pk_mul_f32 v[142:143], v[74:75], v[122:123]
	s_nop 0
	v_add_f32_e32 v142, v142, v145
	v_add_f32_e32 v142, v143, v142
	v_mul_f32_e32 v145, v69, v154
	v_fmac_f32_e32 v145, v68, v153
	v_add_f32_dpp v142, v142, v142 row_ror:8 row_mask:0xf bank_mask:0xf bound_ctrl:1
	v_fmac_f32_e32 v145, v70, v120
	v_fmac_f32_e32 v145, v71, v121
	v_add_f32_dpp v142, v142, v142 row_ror:4 row_mask:0xf bank_mask:0xf bound_ctrl:1
	s_nop 1
	v_add_f32_dpp v190, v142, v142 row_ror:2 row_mask:0xf bank_mask:0xf bound_ctrl:1
	v_pk_mul_f32 v[142:143], v[72:73], v[118:119]
	s_nop 0
	v_add_f32_e32 v142, v142, v145
	v_add_f32_e32 v145, v143, v142
	v_pk_mul_f32 v[142:143], v[74:75], v[116:117]
	v_mov_b32_dpp v191, v190 row_ror:1 row_mask:0xf bank_mask:0xf
	v_add_f32_e32 v142, v142, v145
	v_add_f32_e32 v142, v143, v142
	s_nop 1
	v_add_f32_dpp v142, v142, v142 row_ror:8 row_mask:0xf bank_mask:0xf bound_ctrl:1
	s_nop 1
	v_add_f32_dpp v142, v142, v142 row_ror:4 row_mask:0xf bank_mask:0xf bound_ctrl:1
	s_nop 1
	v_add_f32_dpp v192, v142, v142 row_ror:2 row_mask:0xf bank_mask:0xf bound_ctrl:1
	v_sub_u32_e32 v142, 2, v173
	v_lshl_add_u32 v142, v142, 2, s51
	v_add_u32_e32 v145, 0x2600, v142
	v_pk_mul_f32 v[142:143], v[72:73], v[108:109]
	v_mov_b32_dpp v193, v192 row_ror:1 row_mask:0xf bank_mask:0xf
	v_add_f32_e32 v142, v142, v146
	v_add_f32_e32 v146, v143, v142
	v_pk_mul_f32 v[142:143], v[74:75], v[106:107]
	s_nop 0
	v_add_f32_e32 v142, v142, v146
	v_add_f32_e32 v142, v143, v142
	v_mul_f32_e32 v146, v85, v158
	v_fmac_f32_e32 v146, v84, v157
	v_add_f32_dpp v142, v142, v142 row_ror:8 row_mask:0xf bank_mask:0xf bound_ctrl:1
	s_nop 1
	v_add_f32_dpp v142, v142, v142 row_ror:4 row_mask:0xf bank_mask:0xf bound_ctrl:1
	s_nop 1
	v_add_f32_dpp v197, v142, v142 row_ror:2 row_mask:0xf bank_mask:0xf bound_ctrl:1
	v_pk_mul_f32 v[142:143], v[86:87], v[134:135]
	s_nop 0
	v_add_f32_e32 v142, v142, v146
	v_add_f32_e32 v146, v143, v142
	s_waitcnt vmcnt(2)
	v_pk_mul_f32 v[142:143], v[88:89], v[132:133]
	v_mov_b32_dpp v198, v197 row_ror:1 row_mask:0xf bank_mask:0xf
	v_add_f32_e32 v142, v142, v146
	v_add_f32_e32 v146, v143, v142
	v_pk_mul_f32 v[142:143], v[90:91], v[130:131]
	s_nop 0
	v_add_f32_e32 v142, v142, v146
	v_add_f32_e32 v142, v143, v142
	v_mul_f32_e32 v146, v85, v156
	v_fmac_f32_e32 v146, v84, v155
	v_add_f32_dpp v142, v142, v142 row_ror:8 row_mask:0xf bank_mask:0xf bound_ctrl:1
	s_nop 1
	v_add_f32_dpp v142, v142, v142 row_ror:4 row_mask:0xf bank_mask:0xf bound_ctrl:1
	s_nop 1
	v_add_f32_dpp v199, v142, v142 row_ror:2 row_mask:0xf bank_mask:0xf bound_ctrl:1
	v_lshlrev_b32_e32 v142, 2, v172
	v_sub_u32_e32 v142, s51, v142
	v_add_u32_e32 v211, 0x2600, v142
	v_pk_mul_f32 v[142:143], v[86:87], v[126:127]
	v_mov_b32_dpp v200, v199 row_ror:1 row_mask:0xf bank_mask:0xf
	v_add_f32_e32 v142, v142, v146
	v_add_f32_e32 v146, v143, v142
	v_pk_mul_f32 v[142:143], v[88:89], v[124:125]
	s_nop 0
	v_add_f32_e32 v142, v142, v146
	v_add_f32_e32 v146, v143, v142
	v_pk_mul_f32 v[142:143], v[90:91], v[122:123]
	s_nop 0
	v_add_f32_e32 v142, v142, v146
	v_add_f32_e32 v142, v143, v142
	v_mul_f32_e32 v146, v85, v154
	v_fmac_f32_e32 v146, v84, v153
	v_add_f32_dpp v142, v142, v142 row_ror:8 row_mask:0xf bank_mask:0xf bound_ctrl:1
	s_nop 1
	v_add_f32_dpp v142, v142, v142 row_ror:4 row_mask:0xf bank_mask:0xf bound_ctrl:1
	s_nop 1
	v_add_f32_dpp v201, v142, v142 row_ror:2 row_mask:0xf bank_mask:0xf bound_ctrl:1
	v_pk_mul_f32 v[142:143], v[86:87], v[120:121]
	s_nop 0
	v_add_f32_e32 v142, v142, v146
	v_add_f32_e32 v146, v143, v142
	v_pk_mul_f32 v[142:143], v[88:89], v[118:119]
	v_mov_b32_dpp v202, v201 row_ror:1 row_mask:0xf bank_mask:0xf
	v_add_f32_e32 v142, v142, v146
	v_add_f32_e32 v146, v143, v142
	v_pk_mul_f32 v[142:143], v[90:91], v[116:117]
	s_nop 0
	v_add_f32_e32 v142, v142, v146
	v_add_f32_e32 v142, v143, v142
	s_nop 1
	v_add_f32_dpp v142, v142, v142 row_ror:8 row_mask:0xf bank_mask:0xf bound_ctrl:1
	s_nop 1
	v_add_f32_dpp v142, v142, v142 row_ror:4 row_mask:0xf bank_mask:0xf bound_ctrl:1
	s_nop 1
	v_add_f32_dpp v203, v142, v142 row_ror:2 row_mask:0xf bank_mask:0xf bound_ctrl:1
	v_sub_u32_e32 v142, 2, v172
	v_lshl_add_u32 v142, v142, 2, s51
	v_add_u32_e32 v142, 0x2600, v142
	ds_read2_b32 v[148:149], v144 offset1:1
	ds_read2_b32 v[146:147], v145 offset1:1
	ds_read2_b32 v[144:145], v211 offset1:1
	ds_read2_b32 v[142:143], v142 offset1:1
	v_mul_f32_e32 v211, v85, v152
	v_fmac_f32_e32 v211, v84, v151
	v_add_f32_e32 v211, v212, v211
	v_add_f32_e32 v211, v213, v211
	v_pk_mul_f32 v[212:213], v[88:89], v[108:109]
	v_mov_b32_dpp v210, v203 row_ror:1 row_mask:0xf bank_mask:0xf
	v_add_f32_e32 v211, v212, v211
	v_add_f32_e32 v211, v213, v211
	v_pk_mul_f32 v[212:213], v[90:91], v[106:107]
	s_waitcnt vmcnt(0)
	v_add_f32_e32 v211, v212, v211
	v_add_f32_e32 v211, v213, v211
	v_mov_b32_e32 v212, 0
	s_nop 0
	v_add_f32_dpp v211, v211, v211 row_ror:8 row_mask:0xf bank_mask:0xf bound_ctrl:1
	s_nop 1
	v_add_f32_dpp v211, v211, v211 row_ror:4 row_mask:0xf bank_mask:0xf bound_ctrl:1
	s_nop 1
	v_add_f32_dpp v211, v211, v211 row_ror:2 row_mask:0xf bank_mask:0xf bound_ctrl:1
	s_nop 1
	v_mov_b32_dpp v212, v211 row_ror:1 row_mask:0xf bank_mask:0xf
	v_cmp_lt_i32_e32 vcc, 3, v177
	s_and_saveexec_b64 s[0:1], vcc
	s_cbranch_execz .LBB0_475
	v_add_u32_e32 v177, -4, v177
	v_mad_u64_u32 v[214:215], s[12:13], v177, s19, v[138:139]
	global_store_dwordx4 v[214:215], v[36:39], off nt
	s_nop 1
	v_lshl_add_u64 v[216:217], v[214:215], 0, s[26:27]
	global_store_dwordx4 v[216:217], v[40:43], off nt
	s_nop 1
	v_lshl_add_u64 v[216:217], v[214:215], 0, s[28:29]
	global_store_dwordx4 v[216:217], v[44:47], off nt
	s_nop 1
	v_lshl_add_u64 v[214:215], v[214:215], 0, s[34:35]
	global_store_dwordx4 v[214:215], v[48:51], off nt
	s_nop 1
	s_or_b64 exec, exec, s[0:1]
	v_cmp_lt_i32_e32 vcc, 3, v176
	s_and_saveexec_b64 s[0:1], vcc
	s_cbranch_execnz .LBB0_476
